# FFN gate/up epilogues: the eight per-group row statistic loads issued together behind the first one, one vmcnt wait instead of eight
# speedup vs baseline: 1.0495x; 1.0043x over previous
.LBB0_189:
	v_mov_b32_e32 v144, v150
	v_mov_b32_e32 v146, v1
	s_lshl_b32 s12, s52, 8
	s_add_i32 s12, s12, s66
	v_lshlrev_b32_e32 v142, 4, v146
	v_add_u32_e32 v146, s12, v146
	v_ashrrev_i32_e32 v147, 31, v146
	v_lshl_add_u64 v[148:149], v[146:147], 2, s[6:7]
	global_load_dword v147, v[148:149], off
	global_load_dword v180, v[148:149], off offset:64
	global_load_dword v181, v[148:149], off offset:128
	global_load_dword v182, v[148:149], off offset:192
	global_load_dword v183, v[148:149], off offset:512
	global_load_dword v184, v[148:149], off offset:576
	global_load_dword v185, v[148:149], off offset:640
	global_load_dword v186, v[148:149], off offset:704
	s_lshl_b32 s12, s14, 1
	s_ashr_i32 s13, s12, 31
	s_lshl_b32 s52, s52, 1
	s_ashr_i32 s53, s52, 31
	s_lshl_b64 s[12:13], s[12:13], 22
	s_add_u32 s12, s30, s12
	s_addc_u32 s13, s31, s13
	s_lshl_b64 s[14:15], s[52:53], 14
	s_add_u32 s14, s12, s14
	s_addc_u32 s15, s13, s15
	v_ashrrev_i32_e32 v143, 31, v142
	v_lshlrev_b32_e32 v144, 2, v144
	s_add_u32 s34, s14, s24
	v_ashrrev_i32_e32 v145, 31, v144
	s_addc_u32 s35, s15, s25
	v_lshlrev_b64 v[142:143], 1, v[142:143]
	v_lshlrev_b64 v[144:145], 1, v[144:145]
	s_waitcnt vmcnt(0)
	v_fmamk_f32 v147, v147, 0x3a800000, v155
	v_cmp_gt_f32_e32 vcc, s84, v147
	v_mul_f32_e32 v148, 0x4b800000, v147
	s_nop 0
	v_cndmask_b32_e32 v147, v147, v148, vcc
	v_rsq_f32_e32 v147, v147
	s_nop 0
	v_mul_f32_e32 v148, 0x45800000, v147
	v_cndmask_b32_e32 v156, v147, v148, vcc
	v_pk_mul_f32 v[126:127], v[126:127], v[156:157] op_sel_hi:[1,0]
	v_pk_mul_f32 v[122:123], v[122:123], v[156:157] op_sel_hi:[1,0]
	v_mul_f32_e32 v147, 0xbfb8aa3b, v126
	v_exp_f32_e32 v147, v147
	v_pk_mul_f32 v[124:125], v[124:125], v[156:157] op_sel_hi:[1,0]
	v_lshl_add_u64 v[148:149], s[34:35], 0, v[142:143]
	v_lshl_add_u64 v[148:149], v[148:149], 0, v[144:145]
	v_add_f32_e32 v147, 1.0, v147
	v_rcp_f32_e32 v158, v147
	v_mul_f32_e32 v147, 0xbfb8aa3b, v127
	v_exp_f32_e32 v147, v147
	v_pk_mul_f32 v[118:119], v[118:119], v[156:157] op_sel_hi:[1,0]
	v_pk_mul_f32 v[114:115], v[114:115], v[156:157] op_sel_hi:[1,0]
	v_pk_mul_f32 v[116:117], v[116:117], v[156:157] op_sel_hi:[1,0]
	v_add_f32_e32 v147, 1.0, v147
	v_rcp_f32_e32 v159, v147
	s_add_u32 s34, s14, s36
	s_addc_u32 s35, s15, s37
	s_add_u32 s14, s14, s38
	v_pk_mul_f32 v[126:127], v[126:127], v[158:159]
	s_addc_u32 s15, s15, s39
	v_pk_mul_f32 v[122:123], v[122:123], v[126:127]
	v_pk_mul_f32 v[126:127], v[128:129], v[156:157] op_sel_hi:[1,0]
	v_cvt_pk_bf16_f32 v122, v122, v123
	v_mul_f32_e32 v128, 0xbfb8aa3b, v126
	v_mul_f32_e32 v129, 0xbfb8aa3b, v127
	v_exp_f32_e32 v128, v128
	v_exp_f32_e32 v129, v129
	v_add_f32_e32 v128, 1.0, v128
	v_add_f32_e32 v129, 1.0, v129
	v_rcp_f32_e32 v128, v128
	v_rcp_f32_e32 v129, v129
	s_nop 0
	v_pk_mul_f32 v[126:127], v[126:127], v[128:129]
	s_nop 0
	v_pk_mul_f32 v[124:125], v[124:125], v[126:127]
	s_nop 0
	v_cvt_pk_bf16_f32 v123, v124, v125
	global_store_dwordx2 v[148:149], v[122:123], off
	v_mul_f32_e32 v122, 0xbfb8aa3b, v118
	v_mul_f32_e32 v123, 0xbfb8aa3b, v119
	v_exp_f32_e32 v122, v122
	v_exp_f32_e32 v123, v123
	v_add_f32_e32 v122, 1.0, v122
	v_add_f32_e32 v123, 1.0, v123
	v_rcp_f32_e32 v122, v122
	v_rcp_f32_e32 v123, v123
	s_nop 0
	v_pk_mul_f32 v[118:119], v[118:119], v[122:123]
	s_nop 0
	v_pk_mul_f32 v[114:115], v[114:115], v[118:119]
	v_pk_mul_f32 v[118:119], v[120:121], v[156:157] op_sel_hi:[1,0]
	s_nop 0
	v_mul_f32_e32 v120, 0xbfb8aa3b, v118
	v_mul_f32_e32 v121, 0xbfb8aa3b, v119
	v_exp_f32_e32 v120, v120
	v_exp_f32_e32 v121, v121
	v_add_f32_e32 v120, 1.0, v120
	v_add_f32_e32 v121, 1.0, v121
	v_rcp_f32_e32 v120, v120
	v_rcp_f32_e32 v121, v121
	s_nop 0
	v_pk_mul_f32 v[118:119], v[118:119], v[120:121]
	s_nop 0
	v_pk_mul_f32 v[116:117], v[116:117], v[118:119]
	v_cvt_pk_bf16_f32 v118, v114, v115
	v_cvt_pk_bf16_f32 v119, v116, v117
	v_add_co_u32_e32 v114, vcc, s85, v148
	v_add_u32_e32 v116, 16, v146
	s_nop 0
	v_addc_co_u32_e32 v115, vcc, 0, v149, vcc
	v_ashrrev_i32_e32 v117, 31, v116
	global_store_dwordx2 v[114:115], v[118:119], off
	v_lshl_add_u64 v[116:117], v[116:117], 2, s[6:7]
	v_fmamk_f32 v116, v180, 0x3a800000, v155
	v_cmp_gt_f32_e32 vcc, s84, v116
	v_mul_f32_e32 v117, 0x4b800000, v116
	s_nop 0
	v_cndmask_b32_e32 v116, v116, v117, vcc
	v_rsq_f32_e32 v116, v116
	s_nop 0
	v_mul_f32_e32 v117, 0x45800000, v116
	v_cndmask_b32_e32 v116, v116, v117, vcc
	v_pk_mul_f32 v[110:111], v[110:111], v[116:117] op_sel_hi:[1,0]
	s_nop 0
	v_mul_f32_e32 v117, 0xbfb8aa3b, v110
	v_exp_f32_e32 v117, v117
	s_nop 0
	v_add_f32_e32 v117, 1.0, v117
	v_rcp_f32_e32 v118, v117
	v_mul_f32_e32 v117, 0xbfb8aa3b, v111
	v_exp_f32_e32 v117, v117
	s_nop 0
	v_add_f32_e32 v117, 1.0, v117
	v_rcp_f32_e32 v119, v117
	v_pk_mul_f32 v[106:107], v[106:107], v[116:117] op_sel_hi:[1,0]
	v_pk_mul_f32 v[108:109], v[108:109], v[116:117] op_sel_hi:[1,0]
	v_pk_mul_f32 v[102:103], v[102:103], v[116:117] op_sel_hi:[1,0]
	v_pk_mul_f32 v[110:111], v[110:111], v[118:119]
	v_pk_mul_f32 v[98:99], v[98:99], v[116:117] op_sel_hi:[1,0]
	v_pk_mul_f32 v[106:107], v[106:107], v[110:111]
	v_pk_mul_f32 v[110:111], v[112:113], v[116:117] op_sel_hi:[1,0]
	v_cvt_pk_bf16_f32 v106, v106, v107
	v_mul_f32_e32 v112, 0xbfb8aa3b, v110
	v_mul_f32_e32 v113, 0xbfb8aa3b, v111
	v_exp_f32_e32 v112, v112
	v_exp_f32_e32 v113, v113
	v_pk_mul_f32 v[100:101], v[100:101], v[116:117] op_sel_hi:[1,0]
	v_add_f32_e32 v112, 1.0, v112
	v_add_f32_e32 v113, 1.0, v113
	v_rcp_f32_e32 v112, v112
	v_rcp_f32_e32 v113, v113
	s_nop 0
	v_pk_mul_f32 v[110:111], v[110:111], v[112:113]
	s_nop 0
	v_pk_mul_f32 v[108:109], v[108:109], v[110:111]
	s_nop 0
	v_cvt_pk_bf16_f32 v107, v108, v109
	global_store_dwordx2 v[148:149], v[106:107], off offset:2048
	v_mul_f32_e32 v106, 0xbfb8aa3b, v102
	v_mul_f32_e32 v107, 0xbfb8aa3b, v103
	v_exp_f32_e32 v106, v106
	v_exp_f32_e32 v107, v107
	v_add_f32_e32 v106, 1.0, v106
	v_add_f32_e32 v107, 1.0, v107
	v_rcp_f32_e32 v106, v106
	v_rcp_f32_e32 v107, v107
	s_nop 0
	v_pk_mul_f32 v[102:103], v[102:103], v[106:107]
	s_nop 0
	v_pk_mul_f32 v[98:99], v[98:99], v[102:103]
	v_pk_mul_f32 v[102:103], v[104:105], v[116:117] op_sel_hi:[1,0]
	v_cvt_pk_bf16_f32 v98, v98, v99
	v_mul_f32_e32 v104, 0xbfb8aa3b, v102
	v_mul_f32_e32 v105, 0xbfb8aa3b, v103
	v_exp_f32_e32 v104, v104
	v_exp_f32_e32 v105, v105
	v_add_f32_e32 v104, 1.0, v104
	v_add_f32_e32 v105, 1.0, v105
	v_rcp_f32_e32 v104, v104
	v_rcp_f32_e32 v105, v105
	s_nop 0
	v_pk_mul_f32 v[102:103], v[102:103], v[104:105]
	s_nop 0
	v_pk_mul_f32 v[100:101], v[100:101], v[102:103]
	s_nop 0
	v_cvt_pk_bf16_f32 v99, v100, v101
	global_store_dwordx2 v[114:115], v[98:99], off offset:2048
	v_add_u32_e32 v98, 32, v146
	v_ashrrev_i32_e32 v99, 31, v98
	v_lshl_add_u64 v[98:99], v[98:99], 2, s[6:7]
	v_lshl_add_u64 v[100:101], s[34:35], 0, v[142:143]
	v_lshl_add_u64 v[100:101], v[100:101], 0, v[144:145]
	s_mov_b64 s[34:35], -1
	v_fmamk_f32 v98, v181, 0x3a800000, v155
	v_cmp_gt_f32_e32 vcc, s84, v98
	v_mul_f32_e32 v99, 0x4b800000, v98
	s_nop 0
	v_cndmask_b32_e32 v98, v98, v99, vcc
	v_rsq_f32_e32 v98, v98
	s_nop 0
	v_mul_f32_e32 v99, 0x45800000, v98
	v_cndmask_b32_e32 v98, v98, v99, vcc
	v_pk_mul_f32 v[94:95], v[94:95], v[98:99] op_sel_hi:[1,0]
	s_nop 0
	v_mul_f32_e32 v99, 0xbfb8aa3b, v94
	v_exp_f32_e32 v99, v99
	s_nop 0
	v_add_f32_e32 v99, 1.0, v99
	v_rcp_f32_e32 v102, v99
	v_mul_f32_e32 v99, 0xbfb8aa3b, v95
	v_exp_f32_e32 v99, v99
	s_nop 0
	v_add_f32_e32 v99, 1.0, v99
	v_rcp_f32_e32 v103, v99
	v_pk_mul_f32 v[90:91], v[90:91], v[98:99] op_sel_hi:[1,0]
	v_pk_mul_f32 v[92:93], v[92:93], v[98:99] op_sel_hi:[1,0]
	v_pk_mul_f32 v[86:87], v[86:87], v[98:99] op_sel_hi:[1,0]
	v_pk_mul_f32 v[94:95], v[94:95], v[102:103]
	v_pk_mul_f32 v[82:83], v[82:83], v[98:99] op_sel_hi:[1,0]
	v_pk_mul_f32 v[90:91], v[90:91], v[94:95]
	v_pk_mul_f32 v[94:95], v[96:97], v[98:99] op_sel_hi:[1,0]
	v_cvt_pk_bf16_f32 v90, v90, v91
	v_mul_f32_e32 v96, 0xbfb8aa3b, v94
	v_mul_f32_e32 v97, 0xbfb8aa3b, v95
	v_exp_f32_e32 v96, v96
	v_exp_f32_e32 v97, v97
	v_pk_mul_f32 v[84:85], v[84:85], v[98:99] op_sel_hi:[1,0]
	v_add_f32_e32 v96, 1.0, v96
	v_add_f32_e32 v97, 1.0, v97
	v_rcp_f32_e32 v96, v96
	v_rcp_f32_e32 v97, v97
	s_nop 0
	v_pk_mul_f32 v[94:95], v[94:95], v[96:97]
	s_nop 0
	v_pk_mul_f32 v[92:93], v[92:93], v[94:95]
	s_nop 0
	v_cvt_pk_bf16_f32 v91, v92, v93
	global_store_dwordx2 v[100:101], v[90:91], off
	v_mul_f32_e32 v90, 0xbfb8aa3b, v86
	v_mul_f32_e32 v91, 0xbfb8aa3b, v87
	v_exp_f32_e32 v90, v90
	v_exp_f32_e32 v91, v91
	v_add_f32_e32 v90, 1.0, v90
	v_add_f32_e32 v91, 1.0, v91
	v_rcp_f32_e32 v90, v90
	v_rcp_f32_e32 v91, v91
	s_nop 0
	v_pk_mul_f32 v[86:87], v[86:87], v[90:91]
	s_nop 0
	v_pk_mul_f32 v[82:83], v[82:83], v[86:87]
	v_pk_mul_f32 v[86:87], v[88:89], v[98:99] op_sel_hi:[1,0]
	v_cvt_pk_bf16_f32 v82, v82, v83
	v_mul_f32_e32 v88, 0xbfb8aa3b, v86
	v_mul_f32_e32 v89, 0xbfb8aa3b, v87
	v_exp_f32_e32 v88, v88
	v_exp_f32_e32 v89, v89
	v_add_f32_e32 v88, 1.0, v88
	v_add_f32_e32 v89, 1.0, v89
	v_rcp_f32_e32 v88, v88
	v_rcp_f32_e32 v89, v89
	s_nop 0
	v_pk_mul_f32 v[86:87], v[86:87], v[88:89]
	s_nop 0
	v_pk_mul_f32 v[84:85], v[84:85], v[86:87]
	s_nop 0
	v_cvt_pk_bf16_f32 v83, v84, v85
	v_add_co_u32_e32 v84, vcc, s85, v100
	s_nop 1
	v_addc_co_u32_e32 v85, vcc, 0, v101, vcc
	global_store_dwordx2 v[84:85], v[82:83], off
	v_add_u32_e32 v82, 48, v146
	v_ashrrev_i32_e32 v83, 31, v82
	v_lshl_add_u64 v[82:83], v[82:83], 2, s[6:7]
	v_lshl_add_u64 v[84:85], s[14:15], 0, v[142:143]
	v_lshl_add_u64 v[84:85], v[84:85], 0, v[144:145]
	s_or_b32 s14, s52, 1
	s_ashr_i32 s15, s14, 31
	s_lshl_b64 s[14:15], s[14:15], 14
	s_add_u32 s12, s12, s14
	s_addc_u32 s13, s13, s15
	s_add_u32 s14, s12, s24
	s_addc_u32 s15, s13, s25
	v_fmamk_f32 v82, v182, 0x3a800000, v155
	v_cmp_gt_f32_e32 vcc, s84, v82
	v_mul_f32_e32 v83, 0x4b800000, v82
	s_nop 0
	v_cndmask_b32_e32 v82, v82, v83, vcc
	v_rsq_f32_e32 v82, v82
	s_nop 0
	v_mul_f32_e32 v83, 0x45800000, v82
	v_cndmask_b32_e32 v82, v82, v83, vcc
	v_pk_mul_f32 v[78:79], v[78:79], v[82:83] op_sel_hi:[1,0]
	s_nop 0
	v_mul_f32_e32 v83, 0xbfb8aa3b, v78
	v_exp_f32_e32 v83, v83
	s_nop 0
	v_add_f32_e32 v83, 1.0, v83
	v_rcp_f32_e32 v86, v83
	v_mul_f32_e32 v83, 0xbfb8aa3b, v79
	v_exp_f32_e32 v83, v83
	s_nop 0
	v_add_f32_e32 v83, 1.0, v83
	v_rcp_f32_e32 v87, v83
	v_pk_mul_f32 v[74:75], v[74:75], v[82:83] op_sel_hi:[1,0]
	v_pk_mul_f32 v[76:77], v[76:77], v[82:83] op_sel_hi:[1,0]
	v_pk_mul_f32 v[70:71], v[70:71], v[82:83] op_sel_hi:[1,0]
	v_pk_mul_f32 v[78:79], v[78:79], v[86:87]
	v_pk_mul_f32 v[66:67], v[66:67], v[82:83] op_sel_hi:[1,0]
	v_pk_mul_f32 v[74:75], v[74:75], v[78:79]
	v_pk_mul_f32 v[78:79], v[80:81], v[82:83] op_sel_hi:[1,0]
	v_cvt_pk_bf16_f32 v74, v74, v75
	v_mul_f32_e32 v80, 0xbfb8aa3b, v78
	v_mul_f32_e32 v81, 0xbfb8aa3b, v79
	v_exp_f32_e32 v80, v80
	v_exp_f32_e32 v81, v81
	v_pk_mul_f32 v[68:69], v[68:69], v[82:83] op_sel_hi:[1,0]
	v_add_f32_e32 v80, 1.0, v80
	v_add_f32_e32 v81, 1.0, v81
	v_rcp_f32_e32 v80, v80
	v_rcp_f32_e32 v81, v81
	s_nop 0
	v_pk_mul_f32 v[78:79], v[78:79], v[80:81]
	s_nop 0
	v_pk_mul_f32 v[76:77], v[76:77], v[78:79]
	s_nop 0
	v_cvt_pk_bf16_f32 v75, v76, v77
	global_store_dwordx2 v[84:85], v[74:75], off
	v_mul_f32_e32 v74, 0xbfb8aa3b, v70
	v_mul_f32_e32 v75, 0xbfb8aa3b, v71
	v_exp_f32_e32 v74, v74
	v_exp_f32_e32 v75, v75
	v_add_f32_e32 v74, 1.0, v74
	v_add_f32_e32 v75, 1.0, v75
	v_rcp_f32_e32 v74, v74
	v_rcp_f32_e32 v75, v75
	s_nop 0
	v_pk_mul_f32 v[70:71], v[70:71], v[74:75]
	s_nop 0
	v_pk_mul_f32 v[66:67], v[66:67], v[70:71]
	v_pk_mul_f32 v[70:71], v[72:73], v[82:83] op_sel_hi:[1,0]
	v_cvt_pk_bf16_f32 v66, v66, v67
	v_mul_f32_e32 v72, 0xbfb8aa3b, v70
	v_mul_f32_e32 v73, 0xbfb8aa3b, v71
	v_exp_f32_e32 v72, v72
	v_exp_f32_e32 v73, v73
	v_add_f32_e32 v72, 1.0, v72
	v_add_f32_e32 v73, 1.0, v73
	v_rcp_f32_e32 v72, v72
	v_rcp_f32_e32 v73, v73
	s_nop 0
	v_pk_mul_f32 v[70:71], v[70:71], v[72:73]
	s_nop 0
	v_pk_mul_f32 v[68:69], v[68:69], v[70:71]
	s_nop 0
	v_cvt_pk_bf16_f32 v67, v68, v69
	v_add_co_u32_e32 v68, vcc, s85, v84
	s_nop 1
	v_addc_co_u32_e32 v69, vcc, 0, v85, vcc
	global_store_dwordx2 v[68:69], v[66:67], off
	v_add_u32_e32 v66, 0x80, v146
	v_ashrrev_i32_e32 v67, 31, v66
	v_lshl_add_u64 v[66:67], v[66:67], 2, s[6:7]
	v_fmamk_f32 v66, v183, 0x3a800000, v155
	v_cmp_gt_f32_e32 vcc, s84, v66
	v_mul_f32_e32 v67, 0x4b800000, v66
	s_nop 0
	v_cndmask_b32_e32 v66, v66, v67, vcc
	v_rsq_f32_e32 v66, v66
	s_nop 0
	v_mul_f32_e32 v67, 0x45800000, v66
	v_cndmask_b32_e32 v68, v66, v67, vcc
	v_pk_mul_f32 v[62:63], v[62:63], v[68:69] op_sel_hi:[1,0]
	v_lshl_add_u64 v[66:67], s[14:15], 0, v[142:143]
	v_mul_f32_e32 v69, 0xbfb8aa3b, v62
	v_exp_f32_e32 v69, v69
	v_lshl_add_u64 v[66:67], v[66:67], 0, v[144:145]
	s_add_u32 s14, s12, s36
	s_addc_u32 s15, s13, s37
	v_add_f32_e32 v69, 1.0, v69
	v_rcp_f32_e32 v70, v69
	v_mul_f32_e32 v69, 0xbfb8aa3b, v63
	v_exp_f32_e32 v69, v69
	s_add_u32 s12, s12, s38
	s_addc_u32 s13, s13, s39
	v_add_f32_e32 v69, 1.0, v69
	v_rcp_f32_e32 v71, v69
	v_pk_mul_f32 v[58:59], v[58:59], v[68:69] op_sel_hi:[1,0]
	v_pk_mul_f32 v[60:61], v[60:61], v[68:69] op_sel_hi:[1,0]
	v_pk_mul_f32 v[54:55], v[54:55], v[68:69] op_sel_hi:[1,0]
	v_pk_mul_f32 v[62:63], v[62:63], v[70:71]
	v_pk_mul_f32 v[50:51], v[50:51], v[68:69] op_sel_hi:[1,0]
	v_pk_mul_f32 v[58:59], v[58:59], v[62:63]
	v_pk_mul_f32 v[62:63], v[64:65], v[68:69] op_sel_hi:[1,0]
	v_cvt_pk_bf16_f32 v58, v58, v59
	v_mul_f32_e32 v64, 0xbfb8aa3b, v62
	v_mul_f32_e32 v65, 0xbfb8aa3b, v63
	v_exp_f32_e32 v64, v64
	v_exp_f32_e32 v65, v65
	v_pk_mul_f32 v[52:53], v[52:53], v[68:69] op_sel_hi:[1,0]
	v_add_f32_e32 v64, 1.0, v64
	v_add_f32_e32 v65, 1.0, v65
	v_rcp_f32_e32 v64, v64
	v_rcp_f32_e32 v65, v65
	s_nop 0
	v_pk_mul_f32 v[62:63], v[62:63], v[64:65]
	s_nop 0
	v_pk_mul_f32 v[60:61], v[60:61], v[62:63]
	s_nop 0
	v_cvt_pk_bf16_f32 v59, v60, v61
	global_store_dwordx2 v[66:67], v[58:59], off
	v_mul_f32_e32 v58, 0xbfb8aa3b, v54
	v_mul_f32_e32 v59, 0xbfb8aa3b, v55
	v_exp_f32_e32 v58, v58
	v_exp_f32_e32 v59, v59
	v_add_f32_e32 v58, 1.0, v58
	v_add_f32_e32 v59, 1.0, v59
	v_rcp_f32_e32 v58, v58
	v_rcp_f32_e32 v59, v59
	s_nop 0
	v_pk_mul_f32 v[54:55], v[54:55], v[58:59]
	s_nop 0
	v_pk_mul_f32 v[50:51], v[50:51], v[54:55]
	v_pk_mul_f32 v[54:55], v[56:57], v[68:69] op_sel_hi:[1,0]
	s_nop 0
	v_mul_f32_e32 v56, 0xbfb8aa3b, v54
	v_mul_f32_e32 v57, 0xbfb8aa3b, v55
	v_exp_f32_e32 v56, v56
	v_exp_f32_e32 v57, v57
	v_add_f32_e32 v56, 1.0, v56
	v_add_f32_e32 v57, 1.0, v57
	v_rcp_f32_e32 v56, v56
	v_rcp_f32_e32 v57, v57
	s_nop 0
	v_pk_mul_f32 v[54:55], v[54:55], v[56:57]
	s_nop 0
	v_pk_mul_f32 v[52:53], v[52:53], v[54:55]
	v_cvt_pk_bf16_f32 v54, v50, v51
	v_cvt_pk_bf16_f32 v55, v52, v53
	v_add_co_u32_e32 v50, vcc, s85, v66
	v_add_u32_e32 v52, 0x90, v146
	s_nop 0
	v_addc_co_u32_e32 v51, vcc, 0, v67, vcc
	v_ashrrev_i32_e32 v53, 31, v52
	global_store_dwordx2 v[50:51], v[54:55], off
	v_lshl_add_u64 v[52:53], v[52:53], 2, s[6:7]
	v_fmamk_f32 v52, v184, 0x3a800000, v155
	v_cmp_gt_f32_e32 vcc, s84, v52
	v_mul_f32_e32 v53, 0x4b800000, v52
	s_nop 0
	v_cndmask_b32_e32 v52, v52, v53, vcc
	v_rsq_f32_e32 v52, v52
	s_nop 0
	v_mul_f32_e32 v53, 0x45800000, v52
	v_cndmask_b32_e32 v52, v52, v53, vcc
	v_pk_mul_f32 v[46:47], v[46:47], v[52:53] op_sel_hi:[1,0]
	s_nop 0
	v_mul_f32_e32 v53, 0xbfb8aa3b, v46
	v_exp_f32_e32 v53, v53
	s_nop 0
	v_add_f32_e32 v53, 1.0, v53
	v_rcp_f32_e32 v54, v53
	v_mul_f32_e32 v53, 0xbfb8aa3b, v47
	v_exp_f32_e32 v53, v53
	s_nop 0
	v_add_f32_e32 v53, 1.0, v53
	v_rcp_f32_e32 v55, v53
	v_pk_mul_f32 v[42:43], v[42:43], v[52:53] op_sel_hi:[1,0]
	v_pk_mul_f32 v[44:45], v[44:45], v[52:53] op_sel_hi:[1,0]
	v_pk_mul_f32 v[38:39], v[38:39], v[52:53] op_sel_hi:[1,0]
	v_pk_mul_f32 v[46:47], v[46:47], v[54:55]
	v_pk_mul_f32 v[34:35], v[34:35], v[52:53] op_sel_hi:[1,0]
	v_pk_mul_f32 v[42:43], v[42:43], v[46:47]
	v_pk_mul_f32 v[46:47], v[48:49], v[52:53] op_sel_hi:[1,0]
	v_cvt_pk_bf16_f32 v42, v42, v43
	v_mul_f32_e32 v48, 0xbfb8aa3b, v46
	v_mul_f32_e32 v49, 0xbfb8aa3b, v47
	v_exp_f32_e32 v48, v48
	v_exp_f32_e32 v49, v49
	v_pk_mul_f32 v[36:37], v[36:37], v[52:53] op_sel_hi:[1,0]
	v_add_f32_e32 v48, 1.0, v48
	v_add_f32_e32 v49, 1.0, v49
	v_rcp_f32_e32 v48, v48
	v_rcp_f32_e32 v49, v49
	s_nop 0
	v_pk_mul_f32 v[46:47], v[46:47], v[48:49]
	s_nop 0
	v_pk_mul_f32 v[44:45], v[44:45], v[46:47]
	s_nop 0
	v_cvt_pk_bf16_f32 v43, v44, v45
	global_store_dwordx2 v[66:67], v[42:43], off offset:2048
	v_mul_f32_e32 v42, 0xbfb8aa3b, v38
	v_mul_f32_e32 v43, 0xbfb8aa3b, v39
	v_exp_f32_e32 v42, v42
	v_exp_f32_e32 v43, v43
	v_add_f32_e32 v42, 1.0, v42
	v_add_f32_e32 v43, 1.0, v43
	v_rcp_f32_e32 v42, v42
	v_rcp_f32_e32 v43, v43
	s_nop 0
	v_pk_mul_f32 v[38:39], v[38:39], v[42:43]
	s_nop 0
	v_pk_mul_f32 v[34:35], v[34:35], v[38:39]
	v_pk_mul_f32 v[38:39], v[40:41], v[52:53] op_sel_hi:[1,0]
	v_cvt_pk_bf16_f32 v34, v34, v35
	v_mul_f32_e32 v40, 0xbfb8aa3b, v38
	v_mul_f32_e32 v41, 0xbfb8aa3b, v39
	v_exp_f32_e32 v40, v40
	v_exp_f32_e32 v41, v41
	v_add_f32_e32 v40, 1.0, v40
	v_add_f32_e32 v41, 1.0, v41
	v_rcp_f32_e32 v40, v40
	v_rcp_f32_e32 v41, v41
	s_nop 0
	v_pk_mul_f32 v[38:39], v[38:39], v[40:41]
	s_nop 0
	v_pk_mul_f32 v[36:37], v[36:37], v[38:39]
	s_nop 0
	v_cvt_pk_bf16_f32 v35, v36, v37
	global_store_dwordx2 v[50:51], v[34:35], off offset:2048
	v_add_u32_e32 v34, 0xa0, v146
	v_ashrrev_i32_e32 v35, 31, v34
	v_lshl_add_u64 v[34:35], v[34:35], 2, s[6:7]
	v_lshl_add_u64 v[36:37], s[14:15], 0, v[142:143]
	v_lshl_add_u64 v[36:37], v[36:37], 0, v[144:145]
	v_fmamk_f32 v34, v185, 0x3a800000, v155
	v_cmp_gt_f32_e32 vcc, s84, v34
	v_mul_f32_e32 v35, 0x4b800000, v34
	s_nop 0
	v_cndmask_b32_e32 v34, v34, v35, vcc
	v_rsq_f32_e32 v34, v34
	s_nop 0
	v_mul_f32_e32 v35, 0x45800000, v34
	v_cndmask_b32_e32 v34, v34, v35, vcc
	v_pk_mul_f32 v[30:31], v[30:31], v[34:35] op_sel_hi:[1,0]
	s_nop 0
	v_mul_f32_e32 v35, 0xbfb8aa3b, v30
	v_exp_f32_e32 v35, v35
	s_nop 0
	v_add_f32_e32 v35, 1.0, v35
	v_rcp_f32_e32 v38, v35
	v_mul_f32_e32 v35, 0xbfb8aa3b, v31
	v_exp_f32_e32 v35, v35
	s_nop 0
	v_add_f32_e32 v35, 1.0, v35
	v_rcp_f32_e32 v39, v35
	v_pk_mul_f32 v[26:27], v[26:27], v[34:35] op_sel_hi:[1,0]
	v_pk_mul_f32 v[28:29], v[28:29], v[34:35] op_sel_hi:[1,0]
	v_pk_mul_f32 v[22:23], v[22:23], v[34:35] op_sel_hi:[1,0]
	v_pk_mul_f32 v[30:31], v[30:31], v[38:39]
	v_pk_mul_f32 v[18:19], v[18:19], v[34:35] op_sel_hi:[1,0]
	v_pk_mul_f32 v[26:27], v[26:27], v[30:31]
	v_pk_mul_f32 v[30:31], v[32:33], v[34:35] op_sel_hi:[1,0]
	v_cvt_pk_bf16_f32 v26, v26, v27
	v_mul_f32_e32 v32, 0xbfb8aa3b, v30
	v_mul_f32_e32 v33, 0xbfb8aa3b, v31
	v_exp_f32_e32 v32, v32
	v_exp_f32_e32 v33, v33
	v_pk_mul_f32 v[20:21], v[20:21], v[34:35] op_sel_hi:[1,0]
	v_add_f32_e32 v32, 1.0, v32
	v_add_f32_e32 v33, 1.0, v33
	v_rcp_f32_e32 v32, v32
	v_rcp_f32_e32 v33, v33
	s_nop 0
	v_pk_mul_f32 v[30:31], v[30:31], v[32:33]
	s_nop 0
	v_pk_mul_f32 v[28:29], v[28:29], v[30:31]
	s_nop 0
	v_cvt_pk_bf16_f32 v27, v28, v29
	global_store_dwordx2 v[36:37], v[26:27], off
	v_mul_f32_e32 v26, 0xbfb8aa3b, v22
	v_mul_f32_e32 v27, 0xbfb8aa3b, v23
	v_exp_f32_e32 v26, v26
	v_exp_f32_e32 v27, v27
	v_add_f32_e32 v26, 1.0, v26
	v_add_f32_e32 v27, 1.0, v27
	v_rcp_f32_e32 v26, v26
	v_rcp_f32_e32 v27, v27
	s_nop 0
	v_pk_mul_f32 v[22:23], v[22:23], v[26:27]
	s_nop 0
	v_pk_mul_f32 v[18:19], v[18:19], v[22:23]
	v_pk_mul_f32 v[22:23], v[24:25], v[34:35] op_sel_hi:[1,0]
	v_cvt_pk_bf16_f32 v18, v18, v19
	v_mul_f32_e32 v24, 0xbfb8aa3b, v22
	v_mul_f32_e32 v25, 0xbfb8aa3b, v23
	v_exp_f32_e32 v24, v24
	v_exp_f32_e32 v25, v25
	v_add_f32_e32 v24, 1.0, v24
	v_add_f32_e32 v25, 1.0, v25
	v_rcp_f32_e32 v24, v24
	v_rcp_f32_e32 v25, v25
	s_nop 0
	v_pk_mul_f32 v[22:23], v[22:23], v[24:25]
	s_nop 0
	v_pk_mul_f32 v[20:21], v[20:21], v[22:23]
	s_nop 0
	v_cvt_pk_bf16_f32 v19, v20, v21
	v_add_co_u32_e32 v20, vcc, s85, v36
	s_nop 1
	v_addc_co_u32_e32 v21, vcc, 0, v37, vcc
	global_store_dwordx2 v[20:21], v[18:19], off
	v_add_u32_e32 v18, 0xb0, v146
	v_ashrrev_i32_e32 v19, 31, v18
	v_lshl_add_u64 v[18:19], v[18:19], 2, s[6:7]
	v_lshl_add_u64 v[20:21], s[12:13], 0, v[142:143]
	v_lshl_add_u64 v[20:21], v[20:21], 0, v[144:145]
	v_fmamk_f32 v18, v186, 0x3a800000, v155
	v_cmp_gt_f32_e32 vcc, s84, v18
	v_mul_f32_e32 v19, 0x4b800000, v18
	s_nop 0
	v_cndmask_b32_e32 v18, v18, v19, vcc
	v_rsq_f32_e32 v18, v18
	s_nop 0
	v_mul_f32_e32 v19, 0x45800000, v18
	v_cndmask_b32_e32 v18, v18, v19, vcc
	v_pk_mul_f32 v[14:15], v[14:15], v[18:19] op_sel_hi:[1,0]
	s_nop 0
	v_mul_f32_e32 v19, 0xbfb8aa3b, v14
	v_exp_f32_e32 v19, v19
	s_nop 0
	v_add_f32_e32 v19, 1.0, v19
	v_rcp_f32_e32 v22, v19
	v_mul_f32_e32 v19, 0xbfb8aa3b, v15
	v_exp_f32_e32 v19, v19
	s_nop 0
	v_add_f32_e32 v19, 1.0, v19
	v_rcp_f32_e32 v23, v19
	v_pk_mul_f32 v[10:11], v[10:11], v[18:19] op_sel_hi:[1,0]
	v_pk_mul_f32 v[12:13], v[12:13], v[18:19] op_sel_hi:[1,0]
	v_pk_mul_f32 v[6:7], v[6:7], v[18:19] op_sel_hi:[1,0]
	v_pk_mul_f32 v[14:15], v[14:15], v[22:23]
	v_pk_mul_f32 v[2:3], v[2:3], v[18:19] op_sel_hi:[1,0]
	v_pk_mul_f32 v[10:11], v[10:11], v[14:15]
	v_pk_mul_f32 v[14:15], v[16:17], v[18:19] op_sel_hi:[1,0]
	v_cvt_pk_bf16_f32 v10, v10, v11
	v_mul_f32_e32 v16, 0xbfb8aa3b, v14
	v_mul_f32_e32 v17, 0xbfb8aa3b, v15
	v_exp_f32_e32 v16, v16
	v_exp_f32_e32 v17, v17
	v_pk_mul_f32 v[4:5], v[4:5], v[18:19] op_sel_hi:[1,0]
	v_add_f32_e32 v16, 1.0, v16
	v_add_f32_e32 v17, 1.0, v17
	v_rcp_f32_e32 v16, v16
	v_rcp_f32_e32 v17, v17
	s_nop 0
	v_pk_mul_f32 v[14:15], v[14:15], v[16:17]
	s_nop 0
	v_pk_mul_f32 v[12:13], v[12:13], v[14:15]
	s_nop 0
	v_cvt_pk_bf16_f32 v11, v12, v13
	global_store_dwordx2 v[20:21], v[10:11], off
	v_mul_f32_e32 v10, 0xbfb8aa3b, v6
	v_mul_f32_e32 v11, 0xbfb8aa3b, v7
	v_exp_f32_e32 v10, v10
	v_exp_f32_e32 v11, v11
	v_add_f32_e32 v10, 1.0, v10
	v_add_f32_e32 v11, 1.0, v11
	v_rcp_f32_e32 v10, v10
	v_rcp_f32_e32 v11, v11
	s_nop 0
	v_pk_mul_f32 v[6:7], v[6:7], v[10:11]
	s_nop 0
	v_pk_mul_f32 v[2:3], v[2:3], v[6:7]
	v_pk_mul_f32 v[6:7], v[8:9], v[18:19] op_sel_hi:[1,0]
	v_cvt_pk_bf16_f32 v2, v2, v3
	v_mul_f32_e32 v8, 0xbfb8aa3b, v6
	v_mul_f32_e32 v9, 0xbfb8aa3b, v7
	v_exp_f32_e32 v8, v8
	v_exp_f32_e32 v9, v9
	v_add_f32_e32 v8, 1.0, v8
	v_add_f32_e32 v9, 1.0, v9
	v_rcp_f32_e32 v8, v8
	v_rcp_f32_e32 v9, v9
	s_nop 0
	v_pk_mul_f32 v[6:7], v[6:7], v[8:9]
	s_nop 0
	v_pk_mul_f32 v[4:5], v[4:5], v[6:7]
	s_nop 0
	v_cvt_pk_bf16_f32 v3, v4, v5
	v_add_co_u32_e32 v4, vcc, 0x400000, v20
	s_nop 1
	v_addc_co_u32_e32 v5, vcc, 0, v21, vcc
	s_andn2_b64 vcc, exec, s[4:5]
	global_store_dwordx2 v[4:5], v[2:3], off
	s_cbranch_vccnz .LBB0_182
	s_andn2_b64 vcc, exec, s[0:1]
	s_cbranch_vccnz .LBB0_181
	s_barrier
	s_branch .LBB0_181

.LBB0_1392:
	s_lshl_b32 s12, s0, 8
	v_mov_b32_e32 v144, v148
	v_mov_b32_e32 v145, v1
	s_add_i32 s12, s12, s51
	s_lshl_b32 s34, s1, 1
	v_add_u32_e32 v146, s12, v145
	v_ashrrev_i32_e32 v147, 31, v146
	v_lshl_add_u64 v[142:143], v[146:147], 2, s[10:11]
	global_load_dword v147, v[142:143], off
	global_load_dword v182, v[142:143], off offset:64
	global_load_dword v183, v[142:143], off offset:128
	global_load_dword v184, v[142:143], off offset:192
	global_load_dword v185, v[142:143], off offset:512
	global_load_dword v186, v[142:143], off offset:576
	global_load_dword v187, v[142:143], off offset:640
	global_load_dword v188, v[142:143], off offset:704
	s_lshl_b32 s12, s0, 1
	s_ashr_i32 s35, s34, 31
	s_ashr_i32 s13, s12, 31
	s_lshl_b64 s[0:1], s[34:35], 22
	s_add_u32 s29, s3, s0
	s_addc_u32 s31, s50, s1
	s_lshl_b64 s[0:1], s[12:13], 14
	s_add_u32 s13, s29, s0
	v_lshlrev_b32_e32 v142, 4, v145
	s_addc_u32 s34, s31, s1
	v_lshlrev_b32_e32 v144, 2, v144
	v_ashrrev_i32_e32 v143, 31, v142
	s_add_u32 s0, s13, s22
	v_ashrrev_i32_e32 v145, 31, v144
	v_lshlrev_b64 v[142:143], 1, v[142:143]
	s_addc_u32 s1, s34, s23
	v_lshlrev_b64 v[144:145], 1, v[144:145]
	v_lshl_add_u64 v[156:157], s[0:1], 0, v[142:143]
	v_add_u32_e32 v154, 16, v146
	v_lshl_add_u64 v[156:157], v[156:157], 0, v[144:145]
	v_ashrrev_i32_e32 v155, 31, v154
	v_lshl_add_u64 v[154:155], v[154:155], 2, s[10:11]
	s_waitcnt vmcnt(0)
	v_fmamk_f32 v147, v147, 0x3a800000, v153
	v_mul_f32_e32 v158, 0x4b800000, v147
	v_cmp_gt_f32_e32 vcc, s57, v147
	s_nop 1
	v_cndmask_b32_e32 v147, v147, v158, vcc
	v_rsq_f32_e32 v147, v147
	v_add_co_u32_e64 v158, s[0:1], s58, v156
	v_mul_f32_e32 v160, 0x45800000, v147
	v_cndmask_b32_e32 v160, v147, v160, vcc
	v_pk_mul_f32 v[126:127], v[126:127], v[160:161] op_sel_hi:[1,0]
	v_pk_mul_f32 v[128:129], v[128:129], v[160:161] op_sel_hi:[1,0]
	v_pk_mul_f32 v[122:123], v[122:123], v[160:161] op_sel_hi:[1,0]
	v_pk_mul_f32 v[124:125], v[124:125], v[160:161] op_sel_hi:[1,0]
	v_pk_mul_f32 v[118:119], v[118:119], v[160:161] op_sel_hi:[1,0]
	v_pk_mul_f32 v[114:115], v[114:115], v[160:161] op_sel_hi:[1,0]
	v_pk_mul_f32 v[120:121], v[120:121], v[160:161] op_sel_hi:[1,0]
	v_pk_mul_f32 v[116:117], v[116:117], v[160:161] op_sel_hi:[1,0]
	v_mul_f32_e32 v147, 0xbfb8aa3b, v126
	v_mul_f32_e32 v160, 0xbfb8aa3b, v127
	v_mul_f32_e32 v161, 0xbfb8aa3b, v128
	v_mul_f32_e32 v162, 0xbfb8aa3b, v129
	v_mul_f32_e32 v163, 0xbfb8aa3b, v118
	v_mul_f32_e32 v164, 0xbfb8aa3b, v119
	v_mul_f32_e32 v165, 0xbfb8aa3b, v120
	v_mul_f32_e32 v166, 0xbfb8aa3b, v121
	v_exp_f32_e32 v147, v147
	v_exp_f32_e32 v160, v160
	v_exp_f32_e32 v161, v161
	v_exp_f32_e32 v162, v162
	v_exp_f32_e32 v163, v163
	v_exp_f32_e32 v164, v164
	v_exp_f32_e32 v165, v165
	v_exp_f32_e32 v166, v166
	v_add_f32_e32 v147, 1.0, v147
	v_add_f32_e32 v167, 1.0, v160
	v_add_f32_e32 v168, 1.0, v161
	v_add_f32_e32 v169, 1.0, v162
	v_add_f32_e32 v170, 1.0, v163
	v_add_f32_e32 v171, 1.0, v164
	v_add_f32_e32 v172, 1.0, v165
	v_add_f32_e32 v173, 1.0, v166
	v_rcp_f32_e32 v160, v147
	v_rcp_f32_e32 v161, v167
	v_rcp_f32_e32 v162, v168
	v_rcp_f32_e32 v163, v169
	v_rcp_f32_e32 v164, v170
	v_rcp_f32_e32 v165, v171
	v_rcp_f32_e32 v166, v172
	v_rcp_f32_e32 v167, v173
	v_pk_mul_f32 v[126:127], v[126:127], v[160:161]
	v_pk_mul_f32 v[128:129], v[128:129], v[162:163]
	v_pk_mul_f32 v[118:119], v[118:119], v[164:165]
	v_pk_mul_f32 v[120:121], v[120:121], v[166:167]
	v_pk_mul_f32 v[122:123], v[122:123], v[126:127]
	v_pk_mul_f32 v[124:125], v[124:125], v[128:129]
	v_pk_mul_f32 v[114:115], v[114:115], v[118:119]
	v_pk_mul_f32 v[116:117], v[116:117], v[120:121]
	v_cvt_pk_bf16_f32 v118, v122, v123
	v_cvt_pk_bf16_f32 v119, v124, v125
	v_addc_co_u32_e64 v159, s[0:1], 0, v157, s[0:1]
	v_cvt_pk_bf16_f32 v114, v114, v115
	v_cvt_pk_bf16_f32 v115, v116, v117
	global_store_dwordx2 v[156:157], v[118:119], off
	global_store_dwordx2 v[158:159], v[114:115], off
	s_add_u32 s0, s13, s24
	s_addc_u32 s1, s34, s25
	v_fmamk_f32 v114, v182, 0x3a800000, v153
	v_mul_f32_e32 v115, 0x4b800000, v114
	v_cmp_gt_f32_e32 vcc, s57, v114
	s_nop 1
	v_cndmask_b32_e32 v114, v114, v115, vcc
	v_rsq_f32_e32 v116, v114
	v_add_u32_e32 v114, 32, v146
	v_ashrrev_i32_e32 v115, 31, v114
	v_lshl_add_u64 v[114:115], v[114:115], 2, s[10:11]
	v_mul_f32_e32 v117, 0x45800000, v116
	v_cndmask_b32_e32 v116, v116, v117, vcc
	v_pk_mul_f32 v[110:111], v[110:111], v[116:117] op_sel_hi:[1,0]
	v_pk_mul_f32 v[112:113], v[112:113], v[116:117] op_sel_hi:[1,0]
	v_pk_mul_f32 v[106:107], v[106:107], v[116:117] op_sel_hi:[1,0]
	v_pk_mul_f32 v[108:109], v[108:109], v[116:117] op_sel_hi:[1,0]
	v_pk_mul_f32 v[102:103], v[102:103], v[116:117] op_sel_hi:[1,0]
	v_pk_mul_f32 v[98:99], v[98:99], v[116:117] op_sel_hi:[1,0]
	v_pk_mul_f32 v[104:105], v[104:105], v[116:117] op_sel_hi:[1,0]
	v_pk_mul_f32 v[100:101], v[100:101], v[116:117] op_sel_hi:[1,0]
	v_mul_f32_e32 v116, 0xbfb8aa3b, v110
	v_mul_f32_e32 v117, 0xbfb8aa3b, v111
	v_mul_f32_e32 v118, 0xbfb8aa3b, v112
	v_mul_f32_e32 v119, 0xbfb8aa3b, v113
	v_mul_f32_e32 v120, 0xbfb8aa3b, v102
	v_mul_f32_e32 v121, 0xbfb8aa3b, v103
	v_mul_f32_e32 v122, 0xbfb8aa3b, v104
	v_mul_f32_e32 v123, 0xbfb8aa3b, v105
	v_exp_f32_e32 v116, v116
	v_exp_f32_e32 v117, v117
	v_exp_f32_e32 v118, v118
	v_exp_f32_e32 v119, v119
	v_exp_f32_e32 v120, v120
	v_exp_f32_e32 v121, v121
	v_exp_f32_e32 v122, v122
	v_exp_f32_e32 v123, v123
	v_add_f32_e32 v116, 1.0, v116
	v_add_f32_e32 v117, 1.0, v117
	v_add_f32_e32 v118, 1.0, v118
	v_add_f32_e32 v119, 1.0, v119
	v_add_f32_e32 v120, 1.0, v120
	v_add_f32_e32 v121, 1.0, v121
	v_add_f32_e32 v122, 1.0, v122
	v_add_f32_e32 v123, 1.0, v123
	v_rcp_f32_e32 v116, v116
	v_rcp_f32_e32 v117, v117
	v_rcp_f32_e32 v118, v118
	v_rcp_f32_e32 v119, v119
	v_rcp_f32_e32 v120, v120
	v_rcp_f32_e32 v121, v121
	v_rcp_f32_e32 v122, v122
	v_rcp_f32_e32 v123, v123
	v_pk_mul_f32 v[110:111], v[110:111], v[116:117]
	v_pk_mul_f32 v[112:113], v[112:113], v[118:119]
	v_pk_mul_f32 v[102:103], v[102:103], v[120:121]
	v_pk_mul_f32 v[104:105], v[104:105], v[122:123]
	v_pk_mul_f32 v[106:107], v[106:107], v[110:111]
	v_pk_mul_f32 v[108:109], v[108:109], v[112:113]
	v_pk_mul_f32 v[98:99], v[98:99], v[102:103]
	v_pk_mul_f32 v[100:101], v[100:101], v[104:105]
	v_cvt_pk_bf16_f32 v102, v106, v107
	v_cvt_pk_bf16_f32 v103, v108, v109
	v_cvt_pk_bf16_f32 v98, v98, v99
	v_cvt_pk_bf16_f32 v99, v100, v101
	global_store_dwordx2 v[156:157], v[102:103], off offset:2048
	global_store_dwordx2 v[158:159], v[98:99], off offset:2048
	v_lshl_add_u64 v[100:101], s[0:1], 0, v[142:143]
	v_add_u32_e32 v98, 48, v146
	v_lshl_add_u64 v[100:101], v[100:101], 0, v[144:145]
	v_ashrrev_i32_e32 v99, 31, v98
	v_lshl_add_u64 v[98:99], v[98:99], 2, s[10:11]
	v_fmamk_f32 v102, v183, 0x3a800000, v153
	v_mul_f32_e32 v103, 0x4b800000, v102
	v_cmp_gt_f32_e32 vcc, s57, v102
	s_nop 1
	v_cndmask_b32_e32 v102, v102, v103, vcc
	v_rsq_f32_e32 v104, v102
	v_add_co_u32_e64 v102, s[0:1], s58, v100
	v_mul_f32_e32 v105, 0x45800000, v104
	v_cndmask_b32_e32 v104, v104, v105, vcc
	v_pk_mul_f32 v[94:95], v[94:95], v[104:105] op_sel_hi:[1,0]
	v_pk_mul_f32 v[96:97], v[96:97], v[104:105] op_sel_hi:[1,0]
	v_pk_mul_f32 v[90:91], v[90:91], v[104:105] op_sel_hi:[1,0]
	v_pk_mul_f32 v[92:93], v[92:93], v[104:105] op_sel_hi:[1,0]
	v_pk_mul_f32 v[86:87], v[86:87], v[104:105] op_sel_hi:[1,0]
	v_pk_mul_f32 v[82:83], v[82:83], v[104:105] op_sel_hi:[1,0]
	v_pk_mul_f32 v[88:89], v[88:89], v[104:105] op_sel_hi:[1,0]
	v_pk_mul_f32 v[84:85], v[84:85], v[104:105] op_sel_hi:[1,0]
	v_mul_f32_e32 v104, 0xbfb8aa3b, v94
	v_mul_f32_e32 v105, 0xbfb8aa3b, v95
	v_mul_f32_e32 v106, 0xbfb8aa3b, v96
	v_mul_f32_e32 v107, 0xbfb8aa3b, v97
	v_mul_f32_e32 v108, 0xbfb8aa3b, v86
	v_mul_f32_e32 v109, 0xbfb8aa3b, v87
	v_mul_f32_e32 v110, 0xbfb8aa3b, v88
	v_mul_f32_e32 v111, 0xbfb8aa3b, v89
	v_exp_f32_e32 v104, v104
	v_exp_f32_e32 v105, v105
	v_exp_f32_e32 v106, v106
	v_exp_f32_e32 v107, v107
	v_exp_f32_e32 v108, v108
	v_exp_f32_e32 v109, v109
	v_exp_f32_e32 v110, v110
	v_exp_f32_e32 v111, v111
	v_add_f32_e32 v104, 1.0, v104
	v_add_f32_e32 v105, 1.0, v105
	v_add_f32_e32 v106, 1.0, v106
	v_add_f32_e32 v107, 1.0, v107
	v_add_f32_e32 v108, 1.0, v108
	v_add_f32_e32 v109, 1.0, v109
	v_add_f32_e32 v110, 1.0, v110
	v_add_f32_e32 v111, 1.0, v111
	v_rcp_f32_e32 v104, v104
	v_rcp_f32_e32 v105, v105
	v_rcp_f32_e32 v106, v106
	v_rcp_f32_e32 v107, v107
	v_rcp_f32_e32 v108, v108
	v_rcp_f32_e32 v109, v109
	v_rcp_f32_e32 v110, v110
	v_rcp_f32_e32 v111, v111
	v_pk_mul_f32 v[94:95], v[94:95], v[104:105]
	v_pk_mul_f32 v[96:97], v[96:97], v[106:107]
	v_pk_mul_f32 v[86:87], v[86:87], v[108:109]
	v_pk_mul_f32 v[88:89], v[88:89], v[110:111]
	v_pk_mul_f32 v[90:91], v[90:91], v[94:95]
	v_pk_mul_f32 v[92:93], v[92:93], v[96:97]
	v_pk_mul_f32 v[82:83], v[82:83], v[86:87]
	v_pk_mul_f32 v[84:85], v[84:85], v[88:89]
	v_cvt_pk_bf16_f32 v86, v90, v91
	v_cvt_pk_bf16_f32 v87, v92, v93
	v_addc_co_u32_e64 v103, s[0:1], 0, v101, s[0:1]
	v_cvt_pk_bf16_f32 v82, v82, v83
	v_cvt_pk_bf16_f32 v83, v84, v85
	global_store_dwordx2 v[100:101], v[86:87], off
	global_store_dwordx2 v[102:103], v[82:83], off
	s_add_u32 s0, s13, s26
	s_addc_u32 s1, s34, s27
	v_lshl_add_u64 v[84:85], s[0:1], 0, v[142:143]
	v_add_u32_e32 v82, 0x80, v146
	v_lshl_add_u64 v[84:85], v[84:85], 0, v[144:145]
	v_ashrrev_i32_e32 v83, 31, v82
	v_lshl_add_u64 v[82:83], v[82:83], 2, s[10:11]
	v_fmamk_f32 v86, v184, 0x3a800000, v153
	v_mul_f32_e32 v87, 0x4b800000, v86
	v_cmp_gt_f32_e32 vcc, s57, v86
	s_nop 1
	v_cndmask_b32_e32 v86, v86, v87, vcc
	v_rsq_f32_e32 v88, v86
	v_add_co_u32_e64 v86, s[0:1], s58, v84
	v_mul_f32_e32 v89, 0x45800000, v88
	v_cndmask_b32_e32 v88, v88, v89, vcc
	v_pk_mul_f32 v[78:79], v[78:79], v[88:89] op_sel_hi:[1,0]
	v_pk_mul_f32 v[80:81], v[80:81], v[88:89] op_sel_hi:[1,0]
	v_pk_mul_f32 v[74:75], v[74:75], v[88:89] op_sel_hi:[1,0]
	v_pk_mul_f32 v[76:77], v[76:77], v[88:89] op_sel_hi:[1,0]
	v_pk_mul_f32 v[70:71], v[70:71], v[88:89] op_sel_hi:[1,0]
	v_pk_mul_f32 v[66:67], v[66:67], v[88:89] op_sel_hi:[1,0]
	v_pk_mul_f32 v[72:73], v[72:73], v[88:89] op_sel_hi:[1,0]
	v_pk_mul_f32 v[68:69], v[68:69], v[88:89] op_sel_hi:[1,0]
	v_mul_f32_e32 v88, 0xbfb8aa3b, v78
	v_mul_f32_e32 v89, 0xbfb8aa3b, v79
	v_mul_f32_e32 v90, 0xbfb8aa3b, v80
	v_mul_f32_e32 v91, 0xbfb8aa3b, v81
	v_mul_f32_e32 v92, 0xbfb8aa3b, v70
	v_mul_f32_e32 v93, 0xbfb8aa3b, v71
	v_mul_f32_e32 v94, 0xbfb8aa3b, v72
	v_mul_f32_e32 v95, 0xbfb8aa3b, v73
	v_exp_f32_e32 v88, v88
	v_exp_f32_e32 v89, v89
	v_exp_f32_e32 v90, v90
	v_exp_f32_e32 v91, v91
	v_exp_f32_e32 v92, v92
	v_exp_f32_e32 v93, v93
	v_exp_f32_e32 v94, v94
	v_exp_f32_e32 v95, v95
	v_add_f32_e32 v88, 1.0, v88
	v_add_f32_e32 v89, 1.0, v89
	v_add_f32_e32 v90, 1.0, v90
	v_add_f32_e32 v91, 1.0, v91
	v_add_f32_e32 v92, 1.0, v92
	v_add_f32_e32 v93, 1.0, v93
	v_add_f32_e32 v94, 1.0, v94
	v_add_f32_e32 v95, 1.0, v95
	v_rcp_f32_e32 v88, v88
	v_rcp_f32_e32 v89, v89
	v_rcp_f32_e32 v90, v90
	v_rcp_f32_e32 v91, v91
	v_rcp_f32_e32 v92, v92
	v_rcp_f32_e32 v93, v93
	v_rcp_f32_e32 v94, v94
	v_rcp_f32_e32 v95, v95
	v_pk_mul_f32 v[78:79], v[78:79], v[88:89]
	v_pk_mul_f32 v[80:81], v[80:81], v[90:91]
	v_pk_mul_f32 v[70:71], v[70:71], v[92:93]
	v_pk_mul_f32 v[72:73], v[72:73], v[94:95]
	v_pk_mul_f32 v[74:75], v[74:75], v[78:79]
	v_pk_mul_f32 v[76:77], v[76:77], v[80:81]
	v_pk_mul_f32 v[66:67], v[66:67], v[70:71]
	v_pk_mul_f32 v[68:69], v[68:69], v[72:73]
	v_cvt_pk_bf16_f32 v70, v74, v75
	v_cvt_pk_bf16_f32 v71, v76, v77
	v_addc_co_u32_e64 v87, s[0:1], 0, v85, s[0:1]
	v_cvt_pk_bf16_f32 v66, v66, v67
	v_cvt_pk_bf16_f32 v67, v68, v69
	global_store_dwordx2 v[84:85], v[70:71], off
	global_store_dwordx2 v[86:87], v[66:67], off
	s_or_b32 s0, s12, 1
	s_ashr_i32 s1, s0, 31
	s_lshl_b64 s[0:1], s[0:1], 14
	s_add_u32 s12, s29, s0
	s_addc_u32 s13, s31, s1
	s_add_u32 s0, s12, s22
	s_addc_u32 s1, s13, s23
	v_lshl_add_u64 v[68:69], s[0:1], 0, v[142:143]
	v_add_u32_e32 v66, 0x90, v146
	v_lshl_add_u64 v[68:69], v[68:69], 0, v[144:145]
	v_ashrrev_i32_e32 v67, 31, v66
	v_lshl_add_u64 v[66:67], v[66:67], 2, s[10:11]
	v_fmamk_f32 v70, v185, 0x3a800000, v153
	v_mul_f32_e32 v71, 0x4b800000, v70
	v_cmp_gt_f32_e32 vcc, s57, v70
	s_nop 1
	v_cndmask_b32_e32 v70, v70, v71, vcc
	v_rsq_f32_e32 v72, v70
	v_add_co_u32_e64 v70, s[0:1], s58, v68
	v_mul_f32_e32 v73, 0x45800000, v72
	v_cndmask_b32_e32 v72, v72, v73, vcc
	v_pk_mul_f32 v[62:63], v[62:63], v[72:73] op_sel_hi:[1,0]
	v_pk_mul_f32 v[64:65], v[64:65], v[72:73] op_sel_hi:[1,0]
	v_pk_mul_f32 v[58:59], v[58:59], v[72:73] op_sel_hi:[1,0]
	v_pk_mul_f32 v[60:61], v[60:61], v[72:73] op_sel_hi:[1,0]
	v_pk_mul_f32 v[54:55], v[54:55], v[72:73] op_sel_hi:[1,0]
	v_pk_mul_f32 v[50:51], v[50:51], v[72:73] op_sel_hi:[1,0]
	v_pk_mul_f32 v[56:57], v[56:57], v[72:73] op_sel_hi:[1,0]
	v_pk_mul_f32 v[52:53], v[52:53], v[72:73] op_sel_hi:[1,0]
	v_mul_f32_e32 v72, 0xbfb8aa3b, v62
	v_mul_f32_e32 v73, 0xbfb8aa3b, v63
	v_mul_f32_e32 v74, 0xbfb8aa3b, v64
	v_mul_f32_e32 v75, 0xbfb8aa3b, v65
	v_mul_f32_e32 v76, 0xbfb8aa3b, v54
	v_mul_f32_e32 v77, 0xbfb8aa3b, v55
	v_mul_f32_e32 v78, 0xbfb8aa3b, v56
	v_mul_f32_e32 v79, 0xbfb8aa3b, v57
	v_exp_f32_e32 v72, v72
	v_exp_f32_e32 v73, v73
	v_exp_f32_e32 v74, v74
	v_exp_f32_e32 v75, v75
	v_exp_f32_e32 v76, v76
	v_exp_f32_e32 v77, v77
	v_exp_f32_e32 v78, v78
	v_exp_f32_e32 v79, v79
	v_add_f32_e32 v72, 1.0, v72
	v_add_f32_e32 v73, 1.0, v73
	v_add_f32_e32 v74, 1.0, v74
	v_add_f32_e32 v75, 1.0, v75
	v_add_f32_e32 v76, 1.0, v76
	v_add_f32_e32 v77, 1.0, v77
	v_add_f32_e32 v78, 1.0, v78
	v_add_f32_e32 v79, 1.0, v79
	v_rcp_f32_e32 v72, v72
	v_rcp_f32_e32 v73, v73
	v_rcp_f32_e32 v74, v74
	v_rcp_f32_e32 v75, v75
	v_rcp_f32_e32 v76, v76
	v_rcp_f32_e32 v77, v77
	v_rcp_f32_e32 v78, v78
	v_rcp_f32_e32 v79, v79
	v_pk_mul_f32 v[62:63], v[62:63], v[72:73]
	v_pk_mul_f32 v[64:65], v[64:65], v[74:75]
	v_pk_mul_f32 v[54:55], v[54:55], v[76:77]
	v_pk_mul_f32 v[56:57], v[56:57], v[78:79]
	v_pk_mul_f32 v[58:59], v[58:59], v[62:63]
	v_pk_mul_f32 v[60:61], v[60:61], v[64:65]
	v_pk_mul_f32 v[50:51], v[50:51], v[54:55]
	v_pk_mul_f32 v[52:53], v[52:53], v[56:57]
	v_cvt_pk_bf16_f32 v54, v58, v59
	v_cvt_pk_bf16_f32 v55, v60, v61
	v_addc_co_u32_e64 v71, s[0:1], 0, v69, s[0:1]
	v_cvt_pk_bf16_f32 v50, v50, v51
	v_cvt_pk_bf16_f32 v51, v52, v53
	global_store_dwordx2 v[68:69], v[54:55], off
	global_store_dwordx2 v[70:71], v[50:51], off
	s_add_u32 s0, s12, s24
	s_addc_u32 s1, s13, s25
	v_fmamk_f32 v50, v186, 0x3a800000, v153
	v_mul_f32_e32 v51, 0x4b800000, v50
	v_cmp_gt_f32_e32 vcc, s57, v50
	s_nop 1
	v_cndmask_b32_e32 v50, v50, v51, vcc
	v_rsq_f32_e32 v52, v50
	v_add_u32_e32 v50, 0xa0, v146
	v_ashrrev_i32_e32 v51, 31, v50
	v_lshl_add_u64 v[50:51], v[50:51], 2, s[10:11]
	v_mul_f32_e32 v53, 0x45800000, v52
	v_cndmask_b32_e32 v52, v52, v53, vcc
	v_pk_mul_f32 v[46:47], v[46:47], v[52:53] op_sel_hi:[1,0]
	v_pk_mul_f32 v[48:49], v[48:49], v[52:53] op_sel_hi:[1,0]
	v_pk_mul_f32 v[42:43], v[42:43], v[52:53] op_sel_hi:[1,0]
	v_pk_mul_f32 v[44:45], v[44:45], v[52:53] op_sel_hi:[1,0]
	v_pk_mul_f32 v[38:39], v[38:39], v[52:53] op_sel_hi:[1,0]
	v_pk_mul_f32 v[34:35], v[34:35], v[52:53] op_sel_hi:[1,0]
	v_pk_mul_f32 v[40:41], v[40:41], v[52:53] op_sel_hi:[1,0]
	v_pk_mul_f32 v[36:37], v[36:37], v[52:53] op_sel_hi:[1,0]
	v_mul_f32_e32 v52, 0xbfb8aa3b, v46
	v_mul_f32_e32 v53, 0xbfb8aa3b, v47
	v_mul_f32_e32 v54, 0xbfb8aa3b, v48
	v_mul_f32_e32 v55, 0xbfb8aa3b, v49
	v_mul_f32_e32 v56, 0xbfb8aa3b, v38
	v_mul_f32_e32 v57, 0xbfb8aa3b, v39
	v_mul_f32_e32 v58, 0xbfb8aa3b, v40
	v_mul_f32_e32 v59, 0xbfb8aa3b, v41
	v_exp_f32_e32 v52, v52
	v_exp_f32_e32 v53, v53
	v_exp_f32_e32 v54, v54
	v_exp_f32_e32 v55, v55
	v_exp_f32_e32 v56, v56
	v_exp_f32_e32 v57, v57
	v_exp_f32_e32 v58, v58
	v_exp_f32_e32 v59, v59
	v_add_f32_e32 v52, 1.0, v52
	v_add_f32_e32 v53, 1.0, v53
	v_add_f32_e32 v54, 1.0, v54
	v_add_f32_e32 v55, 1.0, v55
	v_add_f32_e32 v56, 1.0, v56
	v_add_f32_e32 v57, 1.0, v57
	v_add_f32_e32 v58, 1.0, v58
	v_add_f32_e32 v59, 1.0, v59
	v_rcp_f32_e32 v52, v52
	v_rcp_f32_e32 v53, v53
	v_rcp_f32_e32 v54, v54
	v_rcp_f32_e32 v55, v55
	v_rcp_f32_e32 v56, v56
	v_rcp_f32_e32 v57, v57
	v_rcp_f32_e32 v58, v58
	v_rcp_f32_e32 v59, v59
	v_pk_mul_f32 v[46:47], v[46:47], v[52:53]
	v_pk_mul_f32 v[48:49], v[48:49], v[54:55]
	v_pk_mul_f32 v[38:39], v[38:39], v[56:57]
	v_pk_mul_f32 v[40:41], v[40:41], v[58:59]
	v_pk_mul_f32 v[42:43], v[42:43], v[46:47]
	v_pk_mul_f32 v[44:45], v[44:45], v[48:49]
	v_pk_mul_f32 v[34:35], v[34:35], v[38:39]
	v_pk_mul_f32 v[36:37], v[36:37], v[40:41]
	v_cvt_pk_bf16_f32 v38, v42, v43
	v_cvt_pk_bf16_f32 v39, v44, v45
	v_cvt_pk_bf16_f32 v34, v34, v35
	v_cvt_pk_bf16_f32 v35, v36, v37
	global_store_dwordx2 v[68:69], v[38:39], off offset:2048
	global_store_dwordx2 v[70:71], v[34:35], off offset:2048
	v_lshl_add_u64 v[36:37], s[0:1], 0, v[142:143]
	v_add_u32_e32 v34, 0xb0, v146
	v_lshl_add_u64 v[36:37], v[36:37], 0, v[144:145]
	v_ashrrev_i32_e32 v35, 31, v34
	v_lshl_add_u64 v[34:35], v[34:35], 2, s[10:11]
	v_fmamk_f32 v38, v187, 0x3a800000, v153
	v_mul_f32_e32 v39, 0x4b800000, v38
	v_cmp_gt_f32_e32 vcc, s57, v38
	s_nop 1
	v_cndmask_b32_e32 v38, v38, v39, vcc
	v_rsq_f32_e32 v40, v38
	v_add_co_u32_e64 v38, s[0:1], s58, v36
	v_mul_f32_e32 v41, 0x45800000, v40
	v_cndmask_b32_e32 v40, v40, v41, vcc
	v_pk_mul_f32 v[30:31], v[30:31], v[40:41] op_sel_hi:[1,0]
	v_pk_mul_f32 v[32:33], v[32:33], v[40:41] op_sel_hi:[1,0]
	v_pk_mul_f32 v[26:27], v[26:27], v[40:41] op_sel_hi:[1,0]
	v_pk_mul_f32 v[28:29], v[28:29], v[40:41] op_sel_hi:[1,0]
	v_pk_mul_f32 v[22:23], v[22:23], v[40:41] op_sel_hi:[1,0]
	v_pk_mul_f32 v[18:19], v[18:19], v[40:41] op_sel_hi:[1,0]
	v_pk_mul_f32 v[24:25], v[24:25], v[40:41] op_sel_hi:[1,0]
	v_pk_mul_f32 v[20:21], v[20:21], v[40:41] op_sel_hi:[1,0]
	v_mul_f32_e32 v40, 0xbfb8aa3b, v30
	v_mul_f32_e32 v41, 0xbfb8aa3b, v31
	v_mul_f32_e32 v42, 0xbfb8aa3b, v32
	v_mul_f32_e32 v43, 0xbfb8aa3b, v33
	v_mul_f32_e32 v44, 0xbfb8aa3b, v22
	v_mul_f32_e32 v45, 0xbfb8aa3b, v23
	v_mul_f32_e32 v46, 0xbfb8aa3b, v24
	v_mul_f32_e32 v47, 0xbfb8aa3b, v25
	v_exp_f32_e32 v40, v40
	v_exp_f32_e32 v41, v41
	v_exp_f32_e32 v42, v42
	v_exp_f32_e32 v43, v43
	v_exp_f32_e32 v44, v44
	v_exp_f32_e32 v45, v45
	v_exp_f32_e32 v46, v46
	v_exp_f32_e32 v47, v47
	v_add_f32_e32 v40, 1.0, v40
	v_add_f32_e32 v41, 1.0, v41
	v_add_f32_e32 v42, 1.0, v42
	v_add_f32_e32 v43, 1.0, v43
	v_add_f32_e32 v44, 1.0, v44
	v_add_f32_e32 v45, 1.0, v45
	v_add_f32_e32 v46, 1.0, v46
	v_add_f32_e32 v47, 1.0, v47
	v_rcp_f32_e32 v40, v40
	v_rcp_f32_e32 v41, v41
	v_rcp_f32_e32 v42, v42
	v_rcp_f32_e32 v43, v43
	v_rcp_f32_e32 v44, v44
	v_rcp_f32_e32 v45, v45
	v_rcp_f32_e32 v46, v46
	v_rcp_f32_e32 v47, v47
	v_pk_mul_f32 v[30:31], v[30:31], v[40:41]
	v_pk_mul_f32 v[32:33], v[32:33], v[42:43]
	v_pk_mul_f32 v[22:23], v[22:23], v[44:45]
	v_pk_mul_f32 v[24:25], v[24:25], v[46:47]
	v_pk_mul_f32 v[26:27], v[26:27], v[30:31]
	v_pk_mul_f32 v[28:29], v[28:29], v[32:33]
	v_pk_mul_f32 v[18:19], v[18:19], v[22:23]
	v_pk_mul_f32 v[20:21], v[20:21], v[24:25]
	v_cvt_pk_bf16_f32 v22, v26, v27
	v_cvt_pk_bf16_f32 v23, v28, v29
	v_addc_co_u32_e64 v39, s[0:1], 0, v37, s[0:1]
	v_cvt_pk_bf16_f32 v18, v18, v19
	v_cvt_pk_bf16_f32 v19, v20, v21
	global_store_dwordx2 v[36:37], v[22:23], off
	global_store_dwordx2 v[38:39], v[18:19], off
	s_add_u32 s0, s12, s26
	s_addc_u32 s1, s13, s27
	v_lshl_add_u64 v[18:19], s[0:1], 0, v[142:143]
	v_lshl_add_u64 v[18:19], v[18:19], 0, v[144:145]
	v_add_co_u32_e32 v20, vcc, 0x400000, v18
	v_fmamk_f32 v21, v188, 0x3a800000, v153
	v_mul_f32_e32 v22, 0x4b800000, v21
	v_cmp_gt_f32_e64 s[0:1], s57, v21
	s_nop 1
	v_cndmask_b32_e64 v21, v21, v22, s[0:1]
	v_rsq_f32_e32 v22, v21
	v_addc_co_u32_e32 v21, vcc, 0, v19, vcc
	s_andn2_b64 vcc, exec, s[6:7]
	v_mul_f32_e32 v23, 0x45800000, v22
	v_cndmask_b32_e64 v22, v22, v23, s[0:1]
	v_pk_mul_f32 v[14:15], v[14:15], v[22:23] op_sel_hi:[1,0]
	v_pk_mul_f32 v[16:17], v[16:17], v[22:23] op_sel_hi:[1,0]
	v_pk_mul_f32 v[10:11], v[10:11], v[22:23] op_sel_hi:[1,0]
	v_pk_mul_f32 v[12:13], v[12:13], v[22:23] op_sel_hi:[1,0]
	v_pk_mul_f32 v[6:7], v[6:7], v[22:23] op_sel_hi:[1,0]
	v_pk_mul_f32 v[2:3], v[2:3], v[22:23] op_sel_hi:[1,0]
	v_pk_mul_f32 v[8:9], v[8:9], v[22:23] op_sel_hi:[1,0]
	v_pk_mul_f32 v[4:5], v[4:5], v[22:23] op_sel_hi:[1,0]
	v_mul_f32_e32 v22, 0xbfb8aa3b, v14
	v_mul_f32_e32 v23, 0xbfb8aa3b, v15
	v_mul_f32_e32 v24, 0xbfb8aa3b, v16
	v_mul_f32_e32 v25, 0xbfb8aa3b, v17
	v_mul_f32_e32 v26, 0xbfb8aa3b, v6
	v_mul_f32_e32 v27, 0xbfb8aa3b, v7
	v_mul_f32_e32 v28, 0xbfb8aa3b, v8
	v_mul_f32_e32 v29, 0xbfb8aa3b, v9
	v_exp_f32_e32 v22, v22
	v_exp_f32_e32 v23, v23
	v_exp_f32_e32 v24, v24
	v_exp_f32_e32 v25, v25
	v_exp_f32_e32 v26, v26
	v_exp_f32_e32 v27, v27
	v_exp_f32_e32 v28, v28
	v_exp_f32_e32 v29, v29
	v_add_f32_e32 v22, 1.0, v22
	v_add_f32_e32 v23, 1.0, v23
	v_add_f32_e32 v24, 1.0, v24
	v_add_f32_e32 v25, 1.0, v25
	v_add_f32_e32 v26, 1.0, v26
	v_add_f32_e32 v27, 1.0, v27
	v_add_f32_e32 v28, 1.0, v28
	v_add_f32_e32 v29, 1.0, v29
	v_rcp_f32_e32 v22, v22
	v_rcp_f32_e32 v23, v23
	v_rcp_f32_e32 v24, v24
	v_rcp_f32_e32 v25, v25
	v_rcp_f32_e32 v26, v26
	v_rcp_f32_e32 v27, v27
	v_rcp_f32_e32 v28, v28
	v_rcp_f32_e32 v29, v29
	v_pk_mul_f32 v[14:15], v[14:15], v[22:23]
	v_pk_mul_f32 v[16:17], v[16:17], v[24:25]
	v_pk_mul_f32 v[6:7], v[6:7], v[26:27]
	v_pk_mul_f32 v[8:9], v[8:9], v[28:29]
	v_pk_mul_f32 v[10:11], v[10:11], v[14:15]
	v_pk_mul_f32 v[12:13], v[12:13], v[16:17]
	v_pk_mul_f32 v[2:3], v[2:3], v[6:7]
	v_pk_mul_f32 v[4:5], v[4:5], v[8:9]
	v_cvt_pk_bf16_f32 v6, v10, v11
	v_cvt_pk_bf16_f32 v7, v12, v13
	s_mov_b64 s[0:1], -1
	v_cvt_pk_bf16_f32 v2, v2, v3
	v_cvt_pk_bf16_f32 v3, v4, v5
	global_store_dwordx2 v[18:19], v[6:7], off
	global_store_dwordx2 v[20:21], v[2:3], off
	s_cbranch_vccnz .LBB0_1385
	s_andn2_b64 vcc, exec, s[14:15]
	s_cbranch_vccnz .LBB0_1384
	s_barrier
	s_branch .LBB0_1384
